# grid barrier first-use census: 16 counter loads issued together
# speedup vs baseline: 1.0671x; 1.0022x over previous
.LBB0_12:
	v_readlane_b32 s16, v253, 7
	v_readlane_b32 s17, v253, 8
	s_mov_b64 s[18:19], -1
	s_nop 4
	global_load_dword v2, v196, s[16:17] sc1
	global_load_dword v3, v196, s[16:17] offset:256 sc1
	global_load_dword v4, v196, s[16:17] offset:512 sc1
	global_load_dword v5, v196, s[16:17] offset:768 sc1
	global_load_dword v6, v196, s[16:17] offset:1024 sc1
	global_load_dword v7, v196, s[16:17] offset:1280 sc1
	global_load_dword v8, v196, s[16:17] offset:1536 sc1
	global_load_dword v9, v196, s[16:17] offset:1792 sc1
	global_load_dword v10, v196, s[16:17] offset:2048 sc1
	global_load_dword v11, v196, s[16:17] offset:2304 sc1
	global_load_dword v12, v196, s[16:17] offset:2560 sc1
	global_load_dword v13, v196, s[16:17] offset:2816 sc1
	global_load_dword v14, v196, s[16:17] offset:3072 sc1
	global_load_dword v15, v196, s[16:17] offset:3328 sc1
	global_load_dword v16, v196, s[16:17] offset:3584 sc1
	global_load_dword v17, v196, s[16:17] offset:3840 sc1
	s_mov_b64 s[16:17], -1
	s_waitcnt vmcnt(0)
	v_add_u32_e32 v18, v3, v2
	v_add_u32_e32 v18, v18, v4
	v_add_u32_e32 v18, v18, v5
	v_add_u32_e32 v18, v18, v6
	v_add_u32_e32 v18, v18, v7
	v_add_u32_e32 v18, v18, v8
	v_add_u32_e32 v18, v18, v9
	v_add_u32_e32 v18, v18, v10
	v_add_u32_e32 v18, v18, v11
	v_add_u32_e32 v18, v18, v12
	v_add_u32_e32 v18, v18, v13
	v_add_u32_e32 v18, v18, v14
	v_add_u32_e32 v18, v18, v15
	v_add_u32_e32 v18, v18, v16
	v_add_u32_e32 v18, v18, v17
	v_cmp_eq_u32_e32 vcc, s2, v18
	s_cbranch_vccnz .LBB0_11
	s_and_b32 s16, s15, 0xff
	s_cmp_eq_u32 s16, 0
	s_mov_b64 s[16:17], -1
	s_mov_b64 s[36:37], -1
	s_sleep 1
	s_cbranch_scc1 .LBB0_16
	s_and_b64 vcc, exec, s[36:37]
	s_cbranch_vccz .LBB0_11
